# E8 + two s_nop after each PV MFMA in attention-C main loop (pacing test)
# baseline (speedup 1.0000x reference)
.LBB0_722:
	v_lshl_add_u32 v100, s72, 1, v248
	ds_read_b64_tr_b16 v[80:81], v100 offset:24576
	ds_read_b64_tr_b16 v[82:83], v100 offset:25088
	ds_read_b64_tr_b16 v[84:85], v100 offset:25600
	ds_read_b64_tr_b16 v[86:87], v100 offset:26112
	ds_read_b64_tr_b16 v[88:89], v100 offset:28672
	ds_read_b64_tr_b16 v[90:91], v100 offset:29184
	ds_read_b64_tr_b16 v[92:93], v100 offset:29696
	ds_read_b64_tr_b16 v[94:95], v100 offset:30208
	s_waitcnt lgkmcnt(6)
	v_mfma_f32_32x32x16_bf16 v[32:47], v[160:163], v[80:83], v[32:47]
	s_nop 0
	s_nop 0
	v_exp_f32_e32 v128, v128
	v_exp_f32_e32 v129, v129
	ds_read_b64_tr_b16 v[96:97], v100 offset:26624
	ds_read_b64_tr_b16 v[98:99], v100 offset:27136
	s_waitcnt lgkmcnt(4)
	v_mfma_f32_32x32x16_bf16 v[48:63], v[160:163], v[88:91], v[48:63]
	s_nop 0
	s_nop 0
	v_exp_f32_e32 v130, v130
	v_exp_f32_e32 v131, v131
	ds_read_b64_tr_b16 v[88:89], v100 offset:30720
	ds_read_b64_tr_b16 v[90:91], v100 offset:31232
	v_add_u32_e32 v101, s61, v250
	ds_read_b128 v[80:83], v101
	ds_read_b128 v[196:199], v101 offset:512
	v_mfma_f32_32x32x16_bf16 v[32:47], v[152:155], v[84:87], v[32:47]
	s_nop 0
	s_nop 0
	v_exp_f32_e32 v132, v132
	v_exp_f32_e32 v133, v133
	ds_read_b64_tr_b16 v[84:85], v100 offset:27648
	ds_read_b64_tr_b16 v[86:87], v100 offset:28160
	ds_read_b128 v[200:203], v101 offset:2048
	ds_read_b128 v[192:195], v101 offset:2560
	s_waitcnt lgkmcnt(10)
	v_mfma_f32_32x32x16_bf16 v[48:63], v[152:155], v[92:95], v[48:63]
	s_nop 0
	s_nop 0
	v_exp_f32_e32 v134, v134
	v_exp_f32_e32 v135, v135
	ds_read_b64_tr_b16 v[92:93], v100 offset:31744
	ds_read_b64_tr_b16 v[94:95], v100 offset:32256
	ds_read_b128 v[188:191], v101 offset:4096
	ds_read_b128 v[184:187], v101 offset:4608
	s_waitcnt lgkmcnt(12)
	v_mfma_f32_32x32x16_bf16 v[32:47], v[148:151], v[96:99], v[32:47]
	s_nop 0
	s_nop 0
	v_exp_f32_e32 v136, v136
	v_exp_f32_e32 v137, v137
	ds_read_b64_tr_b16 v[96:97], v100 offset:32768
	ds_read_b64_tr_b16 v[98:99], v100 offset:33280
	ds_read_b128 v[180:183], v101 offset:6144
	ds_read_b128 v[176:179], v101 offset:6656
	s_waitcnt lgkmcnt(14)
	v_mfma_f32_32x32x16_bf16 v[48:63], v[148:151], v[88:91], v[48:63]
	s_nop 0
	s_nop 0
	v_exp_f32_e32 v138, v138
	v_exp_f32_e32 v139, v139
	ds_read_b64_tr_b16 v[88:89], v100 offset:36864
	ds_read_b64_tr_b16 v[90:91], v100 offset:37376
	s_waitcnt lgkmcnt(12)
	v_mfma_f32_32x32x16_bf16 v[32:47], v[144:147], v[84:87], v[32:47]
	s_nop 0
	s_nop 0
	v_exp_f32_e32 v140, v140
	v_exp_f32_e32 v141, v141
	ds_read_b64_tr_b16 v[84:85], v100 offset:33792
	ds_read_b64_tr_b16 v[86:87], v100 offset:34304
	s_waitcnt lgkmcnt(10)
	v_mfma_f32_32x32x16_bf16 v[48:63], v[144:147], v[92:95], v[48:63]
	s_nop 0
	s_nop 0
	v_exp_f32_e32 v142, v142
	v_exp_f32_e32 v143, v143
	ds_read_b64_tr_b16 v[92:93], v100 offset:37888
	ds_read_b64_tr_b16 v[94:95], v100 offset:38400
	s_waitcnt lgkmcnt(8)
	v_mfma_f32_32x32x16_bf16 v[16:31], v[160:163], v[96:99], v[16:31]
	s_nop 0
	s_nop 0
	v_exp_f32_e32 v112, v112
	v_exp_f32_e32 v113, v113
	ds_read_b64_tr_b16 v[96:97], v100 offset:34816
	ds_read_b64_tr_b16 v[98:99], v100 offset:35328
	s_waitcnt lgkmcnt(6)
	v_mfma_f32_32x32x16_bf16 v[0:15], v[160:163], v[88:91], v[0:15]
	s_nop 0
	s_nop 0
	v_exp_f32_e32 v114, v114
	v_exp_f32_e32 v115, v115
	ds_read_b64_tr_b16 v[88:89], v100 offset:38912
	ds_read_b64_tr_b16 v[90:91], v100 offset:39424
	s_waitcnt lgkmcnt(6)
	v_mfma_f32_32x32x16_bf16 v[16:31], v[152:155], v[84:87], v[16:31]
	s_nop 0
	s_nop 0
	v_exp_f32_e32 v116, v116
	v_exp_f32_e32 v117, v117
	ds_read_b64_tr_b16 v[84:85], v100 offset:35840
	ds_read_b64_tr_b16 v[86:87], v100 offset:36352
	s_waitcnt lgkmcnt(6)
	v_mfma_f32_32x32x16_bf16 v[0:15], v[152:155], v[92:95], v[0:15]
	s_nop 0
	s_nop 0
	v_exp_f32_e32 v118, v118
	v_exp_f32_e32 v119, v119
	ds_read_b64_tr_b16 v[92:93], v100 offset:39936
	ds_read_b64_tr_b16 v[94:95], v100 offset:40448
	s_waitcnt lgkmcnt(6)
	v_mfma_f32_32x32x16_bf16 v[16:31], v[148:151], v[96:99], v[16:31]
	s_nop 0
	s_nop 0
	v_exp_f32_e32 v120, v120
	v_exp_f32_e32 v121, v121
	s_waitcnt lgkmcnt(4)
	v_mfma_f32_32x32x16_bf16 v[0:15], v[148:151], v[88:91], v[0:15]
	s_nop 0
	s_nop 0
	v_exp_f32_e32 v122, v122
	v_exp_f32_e32 v123, v123
	s_waitcnt lgkmcnt(2)
	v_mfma_f32_32x32x16_bf16 v[16:31], v[144:147], v[84:87], v[16:31]
	s_nop 0
	s_nop 0
	v_exp_f32_e32 v124, v124
	v_exp_f32_e32 v125, v125
	s_waitcnt lgkmcnt(0)
	v_mfma_f32_32x32x16_bf16 v[0:15], v[144:147], v[92:95], v[0:15]
	s_nop 0
	s_nop 0
	v_exp_f32_e32 v126, v126
	v_exp_f32_e32 v127, v127
	s_waitcnt vmcnt(3) lgkmcnt(0)
	s_barrier
	s_andn2_b64 vcc, exec, s[42:43]
	v_add_u32_e32 v211, s7, v251
	s_cbranch_vccnz .LBB0_724
	s_waitcnt lgkmcnt(0)
	ds_read_b128 v[84:87], v211 offset:96
	ds_read_b128 v[88:91], v211 offset:64
	ds_read_b128 v[92:95], v211 offset:32
	ds_read_b128 v[96:99], v211
	s_waitcnt lgkmcnt(3)
	v_pk_mul_f32 v[44:45], v[44:45], v[84:85]
	s_waitcnt lgkmcnt(2)
	v_pk_mul_f32 v[40:41], v[40:41], v[88:89]
	s_waitcnt lgkmcnt(1)
	v_pk_mul_f32 v[36:37], v[36:37], v[92:93]
	v_pk_mul_f32 v[46:47], v[46:47], v[86:87]
	v_pk_mul_f32 v[42:43], v[42:43], v[90:91]
	v_pk_mul_f32 v[38:39], v[38:39], v[94:95]
	s_waitcnt lgkmcnt(0)
	v_pk_mul_f32 v[34:35], v[34:35], v[98:99]
	v_pk_mul_f32 v[32:33], v[32:33], v[96:97]
	v_pk_mul_f32 v[60:61], v[60:61], v[84:85]
	v_pk_mul_f32 v[56:57], v[56:57], v[88:89]
	v_pk_mul_f32 v[52:53], v[52:53], v[92:93]
	v_pk_mul_f32 v[62:63], v[62:63], v[86:87]
	v_pk_mul_f32 v[58:59], v[58:59], v[90:91]
	v_pk_mul_f32 v[54:55], v[54:55], v[94:95]
	v_pk_mul_f32 v[50:51], v[50:51], v[98:99]
	v_pk_mul_f32 v[48:49], v[48:49], v[96:97]
	v_pk_mul_f32 v[28:29], v[28:29], v[84:85]
	v_pk_mul_f32 v[24:25], v[24:25], v[88:89]
	v_pk_mul_f32 v[20:21], v[20:21], v[92:93]
	v_pk_mul_f32 v[30:31], v[30:31], v[86:87]
	v_pk_mul_f32 v[26:27], v[26:27], v[90:91]
	v_pk_mul_f32 v[22:23], v[22:23], v[94:95]
	v_pk_mul_f32 v[18:19], v[18:19], v[98:99]
	v_pk_mul_f32 v[16:17], v[16:17], v[96:97]
	v_pk_mul_f32 v[12:13], v[12:13], v[84:85]
	v_pk_mul_f32 v[8:9], v[8:9], v[88:89]
	v_pk_mul_f32 v[4:5], v[4:5], v[92:93]
	v_pk_mul_f32 v[14:15], v[14:15], v[86:87]
	v_pk_mul_f32 v[10:11], v[10:11], v[90:91]
	v_pk_mul_f32 v[6:7], v[6:7], v[94:95]
	v_pk_mul_f32 v[2:3], v[2:3], v[98:99]
	v_pk_mul_f32 v[0:1], v[0:1], v[96:97]

.LBB0_725:
	v_lshl_add_u32 v128, s71, 1, v248
	ds_read_b64_tr_b16 v[112:113], v128 offset:24576
	ds_read_b64_tr_b16 v[114:115], v128 offset:25088
	ds_read_b64_tr_b16 v[116:117], v128 offset:25600
	ds_read_b64_tr_b16 v[118:119], v128 offset:26112
	ds_read_b64_tr_b16 v[120:121], v128 offset:28672
	ds_read_b64_tr_b16 v[122:123], v128 offset:29184
	ds_read_b64_tr_b16 v[124:125], v128 offset:29696
	ds_read_b64_tr_b16 v[126:127], v128 offset:30208
	s_waitcnt lgkmcnt(6)
	v_mfma_f32_32x32x16_bf16 v[32:47], v[160:163], v[112:115], v[32:47]
	s_nop 0
	s_nop 0
	v_exp_f32_e32 v96, v96
	v_exp_f32_e32 v97, v97
	ds_read_b64_tr_b16 v[112:113], v128 offset:26624
	ds_read_b64_tr_b16 v[114:115], v128 offset:27136
	s_waitcnt lgkmcnt(4)
	v_mfma_f32_32x32x16_bf16 v[48:63], v[160:163], v[120:123], v[48:63]
	s_nop 0
	s_nop 0
	v_exp_f32_e32 v98, v98
	v_exp_f32_e32 v99, v99
	ds_read_b64_tr_b16 v[120:121], v128 offset:30720
	ds_read_b64_tr_b16 v[122:123], v128 offset:31232
	v_add_u32_e32 v129, s65, v250
	ds_read_b128 v[204:207], v129
	ds_read_b128 v[200:203], v129 offset:512
	v_mfma_f32_32x32x16_bf16 v[32:47], v[152:155], v[116:119], v[32:47]
	s_nop 0
	s_nop 0
	v_exp_f32_e32 v100, v100
	v_exp_f32_e32 v101, v101
	ds_read_b64_tr_b16 v[116:117], v128 offset:27648
	ds_read_b64_tr_b16 v[118:119], v128 offset:28160
	ds_read_b128 v[196:199], v129 offset:2048
	ds_read_b128 v[192:195], v129 offset:2560
	s_waitcnt lgkmcnt(10)
	v_mfma_f32_32x32x16_bf16 v[48:63], v[152:155], v[124:127], v[48:63]
	s_nop 0
	s_nop 0
	v_exp_f32_e32 v102, v102
	v_exp_f32_e32 v103, v103
	ds_read_b64_tr_b16 v[124:125], v128 offset:31744
	ds_read_b64_tr_b16 v[126:127], v128 offset:32256
	ds_read_b128 v[188:191], v129 offset:4096
	ds_read_b128 v[184:187], v129 offset:4608
	s_waitcnt lgkmcnt(12)
	v_mfma_f32_32x32x16_bf16 v[32:47], v[148:151], v[112:115], v[32:47]
	s_nop 0
	s_nop 0
	v_exp_f32_e32 v104, v104
	v_exp_f32_e32 v105, v105
	ds_read_b64_tr_b16 v[112:113], v128 offset:32768
	ds_read_b64_tr_b16 v[114:115], v128 offset:33280
	ds_read_b128 v[180:183], v129 offset:6144
	ds_read_b128 v[176:179], v129 offset:6656
	s_waitcnt lgkmcnt(14)
	v_mfma_f32_32x32x16_bf16 v[48:63], v[148:151], v[120:123], v[48:63]
	s_nop 0
	s_nop 0
	v_exp_f32_e32 v106, v106
	v_exp_f32_e32 v107, v107
	ds_read_b64_tr_b16 v[120:121], v128 offset:36864
	ds_read_b64_tr_b16 v[122:123], v128 offset:37376
	s_waitcnt lgkmcnt(12)
	v_mfma_f32_32x32x16_bf16 v[32:47], v[144:147], v[116:119], v[32:47]
	s_nop 0
	s_nop 0
	v_exp_f32_e32 v108, v108
	v_exp_f32_e32 v109, v109
	ds_read_b64_tr_b16 v[116:117], v128 offset:33792
	ds_read_b64_tr_b16 v[118:119], v128 offset:34304
	s_waitcnt lgkmcnt(10)
	v_mfma_f32_32x32x16_bf16 v[48:63], v[144:147], v[124:127], v[48:63]
	s_nop 0
	s_nop 0
	v_exp_f32_e32 v110, v110
	v_exp_f32_e32 v111, v111
	ds_read_b64_tr_b16 v[124:125], v128 offset:37888
	ds_read_b64_tr_b16 v[126:127], v128 offset:38400
	s_waitcnt lgkmcnt(8)
	v_mfma_f32_32x32x16_bf16 v[16:31], v[160:163], v[112:115], v[16:31]
	s_nop 0
	s_nop 0
	v_exp_f32_e32 v80, v80
	v_exp_f32_e32 v81, v81
	ds_read_b64_tr_b16 v[112:113], v128 offset:34816
	ds_read_b64_tr_b16 v[114:115], v128 offset:35328
	s_waitcnt lgkmcnt(6)
	v_mfma_f32_32x32x16_bf16 v[0:15], v[160:163], v[120:123], v[0:15]
	s_nop 0
	s_nop 0
	v_exp_f32_e32 v82, v82
	v_exp_f32_e32 v83, v83
	ds_read_b64_tr_b16 v[120:121], v128 offset:38912
	ds_read_b64_tr_b16 v[122:123], v128 offset:39424
	s_waitcnt lgkmcnt(6)
	v_mfma_f32_32x32x16_bf16 v[16:31], v[152:155], v[116:119], v[16:31]
	s_nop 0
	s_nop 0
	v_exp_f32_e32 v84, v84
	v_exp_f32_e32 v85, v85
	ds_read_b64_tr_b16 v[116:117], v128 offset:35840
	ds_read_b64_tr_b16 v[118:119], v128 offset:36352
	s_waitcnt lgkmcnt(6)
	v_mfma_f32_32x32x16_bf16 v[0:15], v[152:155], v[124:127], v[0:15]
	s_nop 0
	s_nop 0
	v_exp_f32_e32 v86, v86
	v_exp_f32_e32 v87, v87
	ds_read_b64_tr_b16 v[124:125], v128 offset:39936
	ds_read_b64_tr_b16 v[126:127], v128 offset:40448
	s_waitcnt lgkmcnt(6)
	v_mfma_f32_32x32x16_bf16 v[16:31], v[148:151], v[112:115], v[16:31]
	s_nop 0
	s_nop 0
	v_exp_f32_e32 v88, v88
	v_exp_f32_e32 v89, v89
	s_waitcnt lgkmcnt(4)
	v_mfma_f32_32x32x16_bf16 v[0:15], v[148:151], v[120:123], v[0:15]
	s_nop 0
	s_nop 0
	v_exp_f32_e32 v90, v90
	v_exp_f32_e32 v91, v91
	s_waitcnt lgkmcnt(2)
	v_mfma_f32_32x32x16_bf16 v[16:31], v[144:147], v[116:119], v[16:31]
	s_nop 0
	s_nop 0
	v_exp_f32_e32 v92, v92
	v_exp_f32_e32 v93, v93
	s_waitcnt lgkmcnt(0)
	v_mfma_f32_32x32x16_bf16 v[0:15], v[144:147], v[124:127], v[0:15]
	s_nop 0
	s_nop 0
	v_exp_f32_e32 v94, v94
	v_exp_f32_e32 v95, v95
	s_waitcnt vmcnt(3) lgkmcnt(0)
	s_barrier
	s_andn2_b64 vcc, exec, s[42:43]
	s_cbranch_vccnz .LBB0_727
	s_waitcnt lgkmcnt(0)
	ds_read_b128 v[112:115], v211 offset:96
	ds_read_b128 v[116:119], v211 offset:64
	ds_read_b128 v[120:123], v211 offset:32
	ds_read_b128 v[124:127], v211
	s_waitcnt lgkmcnt(3)
	v_pk_mul_f32 v[44:45], v[44:45], v[112:113]
	s_waitcnt lgkmcnt(2)
	v_pk_mul_f32 v[40:41], v[40:41], v[116:117]
	s_waitcnt lgkmcnt(1)
	v_pk_mul_f32 v[36:37], v[36:37], v[120:121]
	v_pk_mul_f32 v[46:47], v[46:47], v[114:115]
	v_pk_mul_f32 v[42:43], v[42:43], v[118:119]
	v_pk_mul_f32 v[38:39], v[38:39], v[122:123]
	s_waitcnt lgkmcnt(0)
	v_pk_mul_f32 v[34:35], v[34:35], v[126:127]
	v_pk_mul_f32 v[32:33], v[32:33], v[124:125]
	v_pk_mul_f32 v[60:61], v[60:61], v[112:113]
	v_pk_mul_f32 v[56:57], v[56:57], v[116:117]
	v_pk_mul_f32 v[52:53], v[52:53], v[120:121]
	v_pk_mul_f32 v[62:63], v[62:63], v[114:115]
	v_pk_mul_f32 v[58:59], v[58:59], v[118:119]
	v_pk_mul_f32 v[54:55], v[54:55], v[122:123]
	v_pk_mul_f32 v[50:51], v[50:51], v[126:127]
	v_pk_mul_f32 v[48:49], v[48:49], v[124:125]
	v_pk_mul_f32 v[28:29], v[28:29], v[112:113]
	v_pk_mul_f32 v[24:25], v[24:25], v[116:117]
	v_pk_mul_f32 v[20:21], v[20:21], v[120:121]
	v_pk_mul_f32 v[30:31], v[30:31], v[114:115]
	v_pk_mul_f32 v[26:27], v[26:27], v[118:119]
	v_pk_mul_f32 v[22:23], v[22:23], v[122:123]
	v_pk_mul_f32 v[18:19], v[18:19], v[126:127]
	v_pk_mul_f32 v[16:17], v[16:17], v[124:125]
	v_pk_mul_f32 v[12:13], v[12:13], v[112:113]
	v_pk_mul_f32 v[8:9], v[8:9], v[116:117]
	v_pk_mul_f32 v[4:5], v[4:5], v[120:121]
	v_pk_mul_f32 v[14:15], v[14:15], v[114:115]
	v_pk_mul_f32 v[10:11], v[10:11], v[118:119]
	v_pk_mul_f32 v[6:7], v[6:7], v[122:123]
	v_pk_mul_f32 v[2:3], v[2:3], v[126:127]
	v_pk_mul_f32 v[0:1], v[0:1], v[124:125]
